# RNN tile loop: static s_setprio 1 for the younger half (waves 4-7), reset at unit end
# baseline (speedup 1.0000x reference)
.LBB0_84:
	s_setprio 0
	s_waitcnt lgkmcnt(0)
	s_barrier
	v_add_u32_e32 v0, v171, v228
	ds_read_u16 v2, v0
	ds_read_u16 v3, v0 offset:272
	v_lshlrev_b64 v[6:7], 12, v[168:169]
	v_lshl_add_u64 v[6:7], s[0:1], 0, v[6:7]
	v_mov_b32_e32 v171, v1
	v_lshl_add_u64 v[6:7], v[6:7], 0, v[170:171]
	s_waitcnt lgkmcnt(0)
	v_lshl_or_b32 v2, v3, 16, v2
	ds_read_u16 v3, v0 offset:544
	ds_read_u16 v4, v0 offset:816
	s_mov_b32 s0, 0xf80000
	v_add_co_u32_e32 v6, vcc, s0, v6
	v_readlane_b32 s0, v253, 1
	s_waitcnt lgkmcnt(0)
	v_lshl_or_b32 v3, v4, 16, v3
	ds_read_u16 v4, v0 offset:1088
	ds_read_u16 v5, v0 offset:1360
	v_addc_co_u32_e32 v7, vcc, 0, v7, vcc
	v_readlane_b32 s1, v253, 2
	s_waitcnt lgkmcnt(0)
	v_lshl_or_b32 v4, v5, 16, v4
	ds_read_u16 v5, v0 offset:1632
	ds_read_u16 v0, v0 offset:1904
	s_waitcnt lgkmcnt(0)
	v_lshl_or_b32 v5, v0, 16, v5
	global_store_dwordx4 v[6:7], v[2:5], off
	s_waitcnt lgkmcnt(0)
	s_barrier
	s_load_dword s0, s[0:1], 0x10
	s_waitcnt lgkmcnt(0)
	s_lshr_b32 s0, s0, 16
	s_cmp_lg_u32 s0, 0
	s_cselect_b64 s[0:1], -1, 0
	s_cmp_lg_u64 s[0:1], 0
	s_addc_u32 s22, s22, s94
	s_cmpk_gt_i32 s22, 0xff
	s_cbranch_scc1 .LBB0_117

.Lrnn_pre_halo:
	s_or_b64 exec, exec, s[10:11]
	v_readfirstlane_b32 s6, v186
	s_nop 3
	s_lshr_b32 s6, s6, 6
	s_cmp_ge_u32 s6, 4
	s_cbranch_scc0 .Lrnn_noprio
	s_setprio 1
.Lrnn_noprio:
	s_branch .LBB0_113
.LBB0_112:
	s_or_b64 exec, exec, s[10:11]
	s_addk_i32 s20, 0x80
	s_mov_b64 s[6:7], 0x80000
	s_cmpk_lg_i32 s20, 0x1080
	v_lshl_add_u64 v[182:183], v[182:183], 0, s[6:7]
	s_cbranch_scc0 .LBB0_84
